# baseline (speedup 1.0000x reference)
; #define LAS __attribute__((address_space(3)))
; template <int DQK, bool BIAS>
; DI void attn_item(LAS unsigned char* lds, const AttItem it) {
;     ...
;         if (active && kt <= cq && kt >= cq - it.band) {
;             const LAS unsigned char* kb_ = lds + buf * BUFB;
;             f32x16 s[2];
; #pragma unroll
;             for (int kb = 0; kb < 2; ++kb)
; #pragma unroll
;                 for (int i = 0; i < 16; ++i) s[kb][i] = 0.f;
;             if (wid < 4) __builtin_amdgcn_s_setprio(2);
;             bf16x8 kf[2][2];
; #pragma unroll
;             for (int kb = 0; kb < 2; ++kb) kf[0][kb] = *(const LAS bf16x8*)(kb_ + kaoff + kb * 32 * KP);
; #pragma unroll
;             for (int ks = 0; ks < NKS; ++ks)
;             {
;               if (ks + 1 < NKS) {
; #pragma unroll
;                 for (int kb = 0; kb < 2; ++kb) kf[(ks + 1) & 1][kb] = *(const LAS bf16x8*)(kb_ + kaoff + kb * 32 * KP + (ks + 1) * 32); }
; #pragma unroll
;               for (int kb = 0; kb < 2; ++kb) s[kb] = __builtin_amdgcn_mfma_f32_32x32x16_bf16(kf[ks & 1][kb], qf[ks], s[kb], 0, 0, 0);
;               __builtin_amdgcn_sched_barrier(0); }
;             __builtin_amdgcn_s_setprio(0);
;             bf16x8 vf[2][4];
; #pragma unroll
;             for (int d = 0; d < 4; ++d) vf[0][d] = *(const LAS bf16x8*)(kb_ + vaoff + d * 32 * VP);
;             __builtin_amdgcn_sched_barrier(0);
;             const int key0 = kt * 64;
;             const bool tail = key0 + 64 > it.L;
;             float mx = NEGF;
;             if (BIAS) {
;                 const int d0 = (it.kpos0 + key0) - (qposw + l31);
;                 const bool farb = (it.kpos0 + key0 + 63) - qposw <= -128;
;                 const float b0 = bl[0];
; #pragma unroll
;                 for (int kb = 0; kb < 2; ++kb)
; #pragma unroll
;                     for (int i = 0; i < 16; ++i) { const int ko = 32 * kb + 16 * (i >> 3) + 8 * h + (i & 7);
;                         float bv = b0; if (!farb) { int rel = d0 + ko; rel = rel < -128 ? -128 : (rel > 128 ? 128 : rel); bv = bl[rel + 128]; }
;                         float v = s[kb][i] + bv; if (tail && key0 + ko >= it.L) v = NEGF; s[kb][i] = v; mx = fmaxf(mx, v); }
.LBB0_1159:
	s_cmp_gt_i32 s0, s35
	s_cselect_b64 s[4:5], -1, 0
	s_or_b64 s[4:5], s[44:45], s[4:5]
	s_cmp_lt_i32 s0, s47
	s_cselect_b64 s[0:1], -1, 0
	s_or_b64 s[0:1], s[4:5], s[0:1]
	s_and_b64 vcc, exec, s[0:1]
	s_cbranch_vccnz .LBB0_1199
	s_andn2_b64 vcc, exec, s[48:49]
	s_cbranch_vccz .LBB0_1162
	s_setprio 2
.LBB0_1162:
	s_mul_i32 s0, s91, 0x8c00
	s_add_i32 s0, s0, 0
	v_add3_u32 v1, s0, v209, v207
	ds_read_b128 v[2:5], v1
	ds_read_b128 v[6:9], v1 offset:32
	s_waitcnt lgkmcnt(1)
	v_mfma_f32_32x32x16_bf16 v[96:111], v[2:5], v[112:115], 0
	ds_read_b128 v[2:5], v1 offset:8704
	ds_read_b128 v[10:13], v1 offset:8736
	s_waitcnt lgkmcnt(1)
	v_mfma_f32_32x32x16_bf16 v[80:95], v[2:5], v[112:115], 0
	v_mfma_f32_32x32x16_bf16 v[96:111], v[6:9], v[116:119], v[96:111]
	ds_read_b128 v[2:5], v1 offset:64
	ds_read_b128 v[6:9], v1 offset:8768
	s_waitcnt lgkmcnt(2)
	v_mfma_f32_32x32x16_bf16 v[80:95], v[10:13], v[116:119], v[80:95]
	s_waitcnt lgkmcnt(1)
	v_mfma_f32_32x32x16_bf16 v[96:111], v[2:5], v[120:123], v[96:111]
	ds_read_b128 v[2:5], v1 offset:96
	ds_read_b128 v[10:13], v1 offset:8800
	s_waitcnt lgkmcnt(2)
	v_mfma_f32_32x32x16_bf16 v[80:95], v[6:9], v[120:123], v[80:95]
	s_waitcnt lgkmcnt(1)
	v_mfma_f32_32x32x16_bf16 v[96:111], v[2:5], v[124:127], v[96:111]
	ds_read_b128 v[2:5], v1 offset:128
	ds_read_b128 v[6:9], v1 offset:8832
	s_waitcnt lgkmcnt(2)
	v_mfma_f32_32x32x16_bf16 v[80:95], v[10:13], v[124:127], v[80:95]
	s_waitcnt lgkmcnt(1)
	v_mfma_f32_32x32x16_bf16 v[96:111], v[2:5], v[128:131], v[96:111]
	ds_read_b128 v[2:5], v1 offset:160
	ds_read_b128 v[10:13], v1 offset:8864
	s_waitcnt lgkmcnt(2)
	v_mfma_f32_32x32x16_bf16 v[80:95], v[6:9], v[128:131], v[80:95]
	s_waitcnt lgkmcnt(1)
	v_mfma_f32_32x32x16_bf16 v[96:111], v[2:5], v[132:135], v[96:111]
	ds_read_b128 v[2:5], v1 offset:192
	ds_read_b128 v[6:9], v1 offset:8896
	s_waitcnt lgkmcnt(2)
	v_mfma_f32_32x32x16_bf16 v[80:95], v[10:13], v[132:135], v[80:95]
	s_waitcnt lgkmcnt(1)
	v_mfma_f32_32x32x16_bf16 v[96:111], v[2:5], v[136:139], v[96:111]
	ds_read_b128 v[2:5], v1 offset:224
	ds_read_b128 v[10:13], v1 offset:8928
	s_waitcnt lgkmcnt(2)
	v_mfma_f32_32x32x16_bf16 v[80:95], v[6:9], v[136:139], v[80:95]
	s_waitcnt lgkmcnt(1)
	v_mfma_f32_32x32x16_bf16 v[96:111], v[2:5], v[140:143], v[96:111]
	s_waitcnt lgkmcnt(0)
	v_mfma_f32_32x32x16_bf16 v[80:95], v[10:13], v[140:143], v[80:95]
	v_add_u32_e32 v1, s0, v208
	v_add_u32_e32 v1, v1, v207
	ds_read_b128 v[160:163], v1 offset:17408
	ds_read_b128 v[10:13], v1 offset:22016
	ds_read_b128 v[6:9], v1 offset:26624
	ds_read_b128 v[2:5], v1 offset:31232
	v_mov_b32_e32 v14, s79
	ds_read_b32 v14, v14
	s_add_i32 s0, s90, s46
	s_add_i32 s0, s0, 63
	s_cmpk_gt_i32 s0, 0xff80
	s_cselect_b64 s[56:57], -1, 0
	s_cmpk_lt_i32 s0, 0xff81
	s_waitcnt lgkmcnt(0)
	v_mov_b32_e32 v15, v14
	s_cbranch_scc1 .LBB0_1164
	v_add_u32_e32 v15, s46, v170
	v_med3_i32 v15, v15, s82, v217
	v_lshl_add_u32 v15, v15, 2, s79
	ds_read_b32 v15, v15 offset:512

; #define LAS __attribute__((address_space(3)))
; template <int DQK, bool BIAS>
; DI void attn_item(LAS unsigned char* lds, const AttItem it) {
;     ...
;         if (active && kt <= cq && kt >= cq - it.band) {
;             const LAS unsigned char* kb_ = lds + buf * BUFB;
;             f32x16 s[2];
; #pragma unroll
;             for (int kb = 0; kb < 2; ++kb)
; #pragma unroll
;                 for (int i = 0; i < 16; ++i) s[kb][i] = 0.f;
;             if (wid < 4) __builtin_amdgcn_s_setprio(2);
;             bf16x8 kf[2][2];
; #pragma unroll
;             for (int kb = 0; kb < 2; ++kb) kf[0][kb] = *(const LAS bf16x8*)(kb_ + kaoff + kb * 32 * KP);
; #pragma unroll
;             for (int ks = 0; ks < NKS; ++ks)
;             {
;               if (ks + 1 < NKS) {
; #pragma unroll
;                 for (int kb = 0; kb < 2; ++kb) kf[(ks + 1) & 1][kb] = *(const LAS bf16x8*)(kb_ + kaoff + kb * 32 * KP + (ks + 1) * 32); }
; #pragma unroll
;               for (int kb = 0; kb < 2; ++kb) s[kb] = __builtin_amdgcn_mfma_f32_32x32x16_bf16(kf[ks & 1][kb], qf[ks], s[kb], 0, 0, 0);
;               __builtin_amdgcn_sched_barrier(0); }
;             __builtin_amdgcn_s_setprio(0);
;             bf16x8 vf[2][4];
; #pragma unroll
;             for (int d = 0; d < 4; ++d) vf[0][d] = *(const LAS bf16x8*)(kb_ + vaoff + d * 32 * VP);
;             __builtin_amdgcn_sched_barrier(0);
;             const int key0 = kt * 64;
;             const bool tail = key0 + 64 > it.L;
;             float mx = NEGF;
;             if (BIAS) {
;                 const int d0 = (it.kpos0 + key0) - (qposw + l31);
;                 const bool farb = (it.kpos0 + key0 + 63) - qposw <= -128;
;                 const float b0 = bl[0];
; #pragma unroll
;                 for (int kb = 0; kb < 2; ++kb)
; #pragma unroll
;                     for (int i = 0; i < 16; ++i) { const int ko = 32 * kb + 16 * (i >> 3) + 8 * h + (i & 7);
;                         float bv = b0; if (!farb) { int rel = d0 + ko; rel = rel < -128 ? -128 : (rel > 128 ? 128 : rel); bv = bl[rel + 128]; }
;                         float v = s[kb][i] + bv; if (tail && key0 + ko >= it.L) v = NEGF; s[kb][i] = v; mx = fmaxf(mx, v); }
;             } else {
; #pragma unroll
;                 for (int kb = 0; kb < 2; ++kb)
; #pragma unroll
;                     for (int i = 0; i < 16; ++i) { const int ko = 32 * kb + 16 * (i >> 3) + 8 * h + (i & 7);
.LBB0_1261:
	s_cmp_gt_i32 s85, s35
	s_cselect_b64 s[0:1], -1, 0
	s_or_b64 s[0:1], s[46:47], s[0:1]
	s_cmp_lt_i32 s85, s39
	s_cselect_b64 s[4:5], -1, 0
	s_or_b64 s[0:1], s[0:1], s[4:5]
	s_and_b64 vcc, exec, s[0:1]
	s_cbranch_vccnz .LBB0_1267
	s_andn2_b64 vcc, exec, s[28:29]
	s_cbranch_vccz .LBB0_1264
	s_setprio 2
.LBB0_1264:
	s_mul_i32 s0, s50, 0xac00
	s_add_i32 s0, s0, 0
	v_add3_u32 v1, s0, v212, v207
	ds_read_b128 v[2:5], v1
	ds_read_b128 v[6:9], v1 offset:32
	s_waitcnt lgkmcnt(1)
	v_mfma_f32_32x32x16_bf16 v[96:111], v[2:5], v[112:115], 0
	ds_read_b128 v[2:5], v1 offset:12800
	ds_read_b128 v[10:13], v1 offset:12832
	s_waitcnt lgkmcnt(1)
	v_mfma_f32_32x32x16_bf16 v[80:95], v[2:5], v[112:115], 0
	v_mfma_f32_32x32x16_bf16 v[96:111], v[6:9], v[116:119], v[96:111]
	ds_read_b128 v[2:5], v1 offset:64
	ds_read_b128 v[6:9], v1 offset:12864
	s_waitcnt lgkmcnt(2)
	v_mfma_f32_32x32x16_bf16 v[80:95], v[10:13], v[116:119], v[80:95]
	s_waitcnt lgkmcnt(1)
	v_mfma_f32_32x32x16_bf16 v[96:111], v[2:5], v[120:123], v[96:111]
	ds_read_b128 v[2:5], v1 offset:96
	ds_read_b128 v[10:13], v1 offset:12896
	s_waitcnt lgkmcnt(2)
	v_mfma_f32_32x32x16_bf16 v[80:95], v[6:9], v[120:123], v[80:95]
	s_waitcnt lgkmcnt(1)
	v_mfma_f32_32x32x16_bf16 v[96:111], v[2:5], v[124:127], v[96:111]
	ds_read_b128 v[2:5], v1 offset:128
	ds_read_b128 v[6:9], v1 offset:12928
	s_waitcnt lgkmcnt(2)
	v_mfma_f32_32x32x16_bf16 v[80:95], v[10:13], v[124:127], v[80:95]
	s_waitcnt lgkmcnt(1)
	v_mfma_f32_32x32x16_bf16 v[96:111], v[2:5], v[128:131], v[96:111]
	ds_read_b128 v[2:5], v1 offset:160
	ds_read_b128 v[10:13], v1 offset:12960
	s_waitcnt lgkmcnt(2)
	v_mfma_f32_32x32x16_bf16 v[80:95], v[6:9], v[128:131], v[80:95]
	s_waitcnt lgkmcnt(1)
	v_mfma_f32_32x32x16_bf16 v[96:111], v[2:5], v[132:135], v[96:111]
	ds_read_b128 v[2:5], v1 offset:192
	ds_read_b128 v[6:9], v1 offset:12992
	s_waitcnt lgkmcnt(2)
	v_mfma_f32_32x32x16_bf16 v[80:95], v[10:13], v[132:135], v[80:95]
	s_waitcnt lgkmcnt(1)
	v_mfma_f32_32x32x16_bf16 v[96:111], v[2:5], v[136:139], v[96:111]
	ds_read_b128 v[2:5], v1 offset:224
	ds_read_b128 v[10:13], v1 offset:13024
	s_waitcnt lgkmcnt(2)
	v_mfma_f32_32x32x16_bf16 v[80:95], v[6:9], v[136:139], v[80:95]
	s_waitcnt lgkmcnt(1)
	v_mfma_f32_32x32x16_bf16 v[96:111], v[2:5], v[140:143], v[96:111]
	ds_read_b128 v[2:5], v1 offset:256
	ds_read_b128 v[6:9], v1 offset:13056
	s_waitcnt lgkmcnt(2)
	v_mfma_f32_32x32x16_bf16 v[80:95], v[10:13], v[140:143], v[80:95]
	s_waitcnt lgkmcnt(1)
	v_mfma_f32_32x32x16_bf16 v[96:111], v[2:5], v[144:147], v[96:111]
	ds_read_b128 v[2:5], v1 offset:288
	ds_read_b128 v[10:13], v1 offset:13088
	s_waitcnt lgkmcnt(2)
	v_mfma_f32_32x32x16_bf16 v[80:95], v[6:9], v[144:147], v[80:95]
	s_waitcnt lgkmcnt(1)
	v_mfma_f32_32x32x16_bf16 v[96:111], v[2:5], v[148:151], v[96:111]
	ds_read_b128 v[2:5], v1 offset:320
	ds_read_b128 v[6:9], v1 offset:13120
	s_waitcnt lgkmcnt(2)
	v_mfma_f32_32x32x16_bf16 v[80:95], v[10:13], v[148:151], v[80:95]
	s_waitcnt lgkmcnt(1)
	v_mfma_f32_32x32x16_bf16 v[96:111], v[2:5], v[152:155], v[96:111]
	ds_read_b128 v[2:5], v1 offset:352
	ds_read_b128 v[10:13], v1 offset:13152
	s_waitcnt lgkmcnt(2)
	v_mfma_f32_32x32x16_bf16 v[80:95], v[6:9], v[152:155], v[80:95]
	s_waitcnt lgkmcnt(1)
	v_mfma_f32_32x32x16_bf16 v[96:111], v[2:5], v[156:159], v[96:111]
	s_waitcnt lgkmcnt(0)
	v_mfma_f32_32x32x16_bf16 v[80:95], v[10:13], v[156:159], v[80:95]
	v_add_u32_e32 v1, s0, v208
	v_add_u32_e32 v1, v1, v207
	ds_read_b128 v[180:183], v1 offset:25600
	ds_read_b128 v[10:13], v1 offset:30208
	ds_read_b128 v[6:9], v1 offset:34816
	ds_read_b128 v[2:5], v1 offset:39424
	v_add_u32_e32 v230, s38, v188
	s_cmp_gt_i32 s38, s51
	v_cmp_gt_i32_e32 vcc, s16, v230
	v_add_u32_e32 v15, 2, v230
	s_nop 0
	v_cndmask_b32_e32 v14, v218, v96, vcc
	s_cselect_b64 vcc, -1, 0
	v_cndmask_b32_e32 v224, v96, v14, vcc
	v_add_u32_e32 v14, 1, v230
	v_cmp_gt_i32_e64 s[8:9], s16, v14
	s_nop 1
	v_cndmask_b32_e64 v14, v218, v97, s[8:9]
	v_cmp_gt_i32_e64 s[8:9], s16, v15
	v_cndmask_b32_e32 v225, v97, v14, vcc
	v_max3_f32 v14, v224, s83, v225
	v_cndmask_b32_e64 v15, v218, v98, s[8:9]
	v_cndmask_b32_e32 v228, v98, v15, vcc
	v_add_u32_e32 v15, 3, v230
	v_cmp_gt_i32_e64 s[8:9], s16, v15
	s_nop 1
	v_cndmask_b32_e64 v15, v218, v99, s[8:9]
	v_cndmask_b32_e32 v229, v99, v15, vcc
	v_add_u32_e32 v15, 4, v230
	v_cmp_gt_i32_e64 s[8:9], s16, v15
	v_max3_f32 v14, v14, v228, v229
	s_nop 0
	v_cndmask_b32_e64 v15, v218, v100, s[8:9]
	v_cndmask_b32_e32 v222, v100, v15, vcc
	v_add_u32_e32 v15, 5, v230
	v_cmp_gt_i32_e64 s[8:9], s16, v15
	s_nop 1
	v_cndmask_b32_e64 v15, v218, v101, s[8:9]
	v_cndmask_b32_e32 v223, v101, v15, vcc
	v_add_u32_e32 v15, 6, v230
	v_cmp_gt_i32_e64 s[8:9], s16, v15
	v_max3_f32 v14, v14, v222, v223
	s_nop 0
	v_cndmask_b32_e64 v15, v218, v102, s[8:9]
	v_cndmask_b32_e32 v226, v102, v15, vcc
	v_add_u32_e32 v15, 7, v230
	v_cmp_gt_i32_e64 s[8:9], s16, v15
	s_nop 1
	v_cndmask_b32_e64 v15, v218, v103, s[8:9]
	v_cndmask_b32_e32 v227, v103, v15, vcc
	v_add_u32_e32 v15, 16, v230
	v_cmp_gt_i32_e64 s[8:9], s16, v15
	v_max3_f32 v14, v14, v226, v227
	s_nop 0
	v_cndmask_b32_e64 v15, v218, v104, s[8:9]
	v_cndmask_b32_e32 v100, v104, v15, vcc
	v_add_u32_e32 v15, 17, v230
	v_cmp_gt_i32_e64 s[8:9], s16, v15
	s_nop 1
	v_cndmask_b32_e64 v15, v218, v105, s[8:9]
	v_cndmask_b32_e32 v101, v105, v15, vcc
	v_add_u32_e32 v15, 18, v230
	v_cmp_gt_i32_e64 s[8:9], s16, v15
	v_max3_f32 v14, v14, v100, v101
	s_nop 0
	v_cndmask_b32_e64 v15, v218, v106, s[8:9]
	v_cndmask_b32_e32 v104, v106, v15, vcc
	v_add_u32_e32 v15, 19, v230
	v_cmp_gt_i32_e64 s[8:9], s16, v15
	s_nop 1
	v_cndmask_b32_e64 v15, v218, v107, s[8:9]
	v_cndmask_b32_e32 v105, v107, v15, vcc
; template <int DQK, bool BIAS>
; DI void attn_item(LAS unsigned char* lds, const AttItem it) {
;     ...
;                     for (int i = 0; i < 16; ++i) { const int ko = 32 * kb + 16 * (i >> 3) + 8 * h + (i & 7);
;                         float v = s[kb][i]; if (tail && key0 + ko >= it.L) v = NEGF; s[kb][i] = v; mx = fmaxf(mx, v); }
;             }
;             mx = fmaxf(mx, __shfl_xor(mx, 32));
;             float m_new = m_run;
;             if (__builtin_amdgcn_ballot_w64(mx > m_run + 6.0f) != 0ull) {
;                 m_new = fmaxf(m_run, mx); const float alpha = __builtin_amdgcn_exp2f(m_run - m_new); m_run = m_new; l_run *= alpha;
; #pragma unroll
;                 for (int d = 0; d < 4; ++d)
; #pragma unroll
;                     for (int i = 0; i < 16; ++i) oacc[d][i] *= alpha;
	v_add_u32_e32 v15, 20, v230
	v_cmp_gt_i32_e64 s[8:9], s16, v15
	v_max3_f32 v14, v14, v104, v105
	s_nop 0
	v_cndmask_b32_e64 v15, v218, v108, s[8:9]
	v_cndmask_b32_e32 v97, v108, v15, vcc
	v_add_u32_e32 v15, 21, v230
	v_cmp_gt_i32_e64 s[8:9], s16, v15
	s_nop 1
	v_cndmask_b32_e64 v15, v218, v109, s[8:9]
	v_cndmask_b32_e32 v98, v109, v15, vcc
	v_add_u32_e32 v15, 22, v230
	v_cmp_gt_i32_e64 s[8:9], s16, v15
	v_max3_f32 v14, v14, v97, v98
	s_nop 0
	v_cndmask_b32_e64 v15, v218, v110, s[8:9]
	v_cndmask_b32_e32 v102, v110, v15, vcc
	v_add_u32_e32 v15, 23, v230
	v_cmp_gt_i32_e64 s[8:9], s16, v15
	s_nop 1
	v_cndmask_b32_e64 v15, v218, v111, s[8:9]
	v_cndmask_b32_e32 v103, v111, v15, vcc
	v_add_u32_e32 v15, 32, v230
	v_cmp_gt_i32_e64 s[8:9], s16, v15
	v_max3_f32 v14, v14, v102, v103
	s_nop 0
	v_cndmask_b32_e64 v15, v218, v80, s[8:9]
	v_cndmask_b32_e32 v96, v80, v15, vcc
	v_add_u32_e32 v15, 33, v230
	v_cmp_gt_i32_e64 s[8:9], s16, v15
	s_nop 1
	v_cndmask_b32_e64 v15, v218, v81, s[8:9]
	v_cndmask_b32_e32 v99, v81, v15, vcc
	v_add_u32_e32 v15, 34, v230
	v_cmp_gt_i32_e64 s[8:9], s16, v15
	v_max3_f32 v14, v14, v96, v99
	v_add_u32_e32 v81, 51, v230
	v_cndmask_b32_e64 v15, v218, v82, s[8:9]
	v_cndmask_b32_e32 v106, v82, v15, vcc
	v_add_u32_e32 v15, 35, v230
	v_cmp_gt_i32_e64 s[8:9], s16, v15
	s_nop 1
	v_cndmask_b32_e64 v15, v218, v83, s[8:9]
	v_cndmask_b32_e32 v107, v83, v15, vcc
	v_add_u32_e32 v15, 36, v230
	v_cmp_gt_i32_e64 s[8:9], s16, v15
	v_max3_f32 v14, v14, v106, v107
	v_add_u32_e32 v83, 53, v230
	v_cndmask_b32_e64 v15, v218, v84, s[8:9]
	v_cndmask_b32_e32 v108, v84, v15, vcc
	v_add_u32_e32 v15, 37, v230
	v_cmp_gt_i32_e64 s[8:9], s16, v15
	s_nop 1
	v_cndmask_b32_e64 v15, v218, v85, s[8:9]
	v_cndmask_b32_e32 v109, v85, v15, vcc
	v_add_u32_e32 v15, 38, v230
	v_cmp_gt_i32_e64 s[8:9], s16, v15
	v_max3_f32 v14, v14, v108, v109
	v_add_u32_e32 v85, 55, v230
	v_cndmask_b32_e64 v15, v218, v86, s[8:9]
	v_cndmask_b32_e32 v86, v86, v15, vcc
	v_add_u32_e32 v15, 39, v230
	v_cmp_gt_i32_e64 s[8:9], s16, v15
	s_nop 1
	v_cndmask_b32_e64 v15, v218, v87, s[8:9]
	v_cndmask_b32_e32 v87, v87, v15, vcc
	v_max3_f32 v80, v14, v86, v87
	v_add_u32_e32 v14, 48, v230
	v_cmp_gt_i32_e64 s[8:9], s16, v14
	v_add_u32_e32 v15, 49, v230
	s_nop 0
	v_cndmask_b32_e64 v14, v218, v88, s[8:9]
	v_cmp_gt_i32_e64 s[8:9], s16, v15
	v_cndmask_b32_e32 v14, v88, v14, vcc
	s_nop 0
	v_cndmask_b32_e64 v15, v218, v89, s[8:9]
	v_cndmask_b32_e32 v15, v89, v15, vcc
	v_max3_f32 v82, v80, v14, v15
	v_add_u32_e32 v80, 50, v230
	v_cmp_gt_i32_e64 s[8:9], s16, v80
	v_xor_b32_e32 v89, 32, v219
	s_nop 0
	v_cndmask_b32_e64 v80, v218, v90, s[8:9]
	v_cmp_gt_i32_e64 s[8:9], s16, v81
	v_cndmask_b32_e32 v80, v90, v80, vcc
	v_and_b32_e32 v90, 64, v219
	v_cndmask_b32_e64 v81, v218, v91, s[8:9]
	v_cndmask_b32_e32 v81, v91, v81, vcc
	v_max3_f32 v84, v82, v80, v81
	v_add_u32_e32 v82, 52, v230
	v_cmp_gt_i32_e64 s[8:9], s16, v82
	v_add_u32_e32 v90, 64, v90
	s_nop 0
	v_cndmask_b32_e64 v82, v218, v92, s[8:9]
	v_cmp_gt_i32_e64 s[8:9], s16, v83
	v_cndmask_b32_e32 v82, v92, v82, vcc
	s_nop 0
	v_cndmask_b32_e64 v83, v218, v93, s[8:9]
	v_cndmask_b32_e32 v83, v93, v83, vcc
	v_max3_f32 v88, v84, v82, v83
	v_add_u32_e32 v84, 54, v230
	v_cmp_gt_i32_e64 s[8:9], s16, v84
	s_nop 1
	v_cndmask_b32_e64 v84, v218, v94, s[8:9]
	v_cmp_gt_i32_e64 s[8:9], s16, v85
	v_cndmask_b32_e32 v84, v94, v84, vcc
	s_nop 0
	v_cndmask_b32_e64 v85, v218, v95, s[8:9]
	v_cndmask_b32_e32 v85, v95, v85, vcc
	v_cmp_lt_i32_e32 vcc, v89, v90
	v_max3_f32 v88, v88, v84, v85
	s_nop 0
	v_cndmask_b32_e32 v89, v219, v89, vcc
	v_lshlrev_b32_e32 v89, 2, v89
	ds_bpermute_b32 v89, v89, v88
	s_waitcnt lgkmcnt(0)
	v_max_f32_e32 v89, v89, v89
	v_max_f32_e32 v88, v88, v89
	v_add_f32_e32 v89, 0x40c00000, v221
	v_cmp_gt_f32_e32 vcc, v88, v89
	s_cbranch_vccz .LBB0_1266
	v_max_f32_e32 v88, v88, v88
	v_max_f32_e32 v89, v221, v221
	v_max_f32_e32 v89, v89, v88
	v_sub_f32_e32 v88, v221, v89
	v_exp_f32_e32 v88, v88
	v_mov_b32_e32 v221, v89
	v_pk_mul_f32 v[78:79], v[78:79], v[88:89] op_sel_hi:[1,0]
	v_pk_mul_f32 v[76:77], v[76:77], v[88:89] op_sel_hi:[1,0]
	v_pk_mul_f32 v[74:75], v[74:75], v[88:89] op_sel_hi:[1,0]
	v_pk_mul_f32 v[72:73], v[72:73], v[88:89] op_sel_hi:[1,0]
	v_pk_mul_f32 v[70:71], v[70:71], v[88:89] op_sel_hi:[1,0]
	v_pk_mul_f32 v[68:69], v[68:69], v[88:89] op_sel_hi:[1,0]
	v_pk_mul_f32 v[66:67], v[66:67], v[88:89] op_sel_hi:[1,0]
	v_pk_mul_f32 v[64:65], v[64:65], v[88:89] op_sel_hi:[1,0]
	v_pk_mul_f32 v[62:63], v[62:63], v[88:89] op_sel_hi:[1,0]
	v_pk_mul_f32 v[60:61], v[60:61], v[88:89] op_sel_hi:[1,0]
	v_pk_mul_f32 v[58:59], v[58:59], v[88:89] op_sel_hi:[1,0]
	v_pk_mul_f32 v[56:57], v[56:57], v[88:89] op_sel_hi:[1,0]
	v_pk_mul_f32 v[54:55], v[54:55], v[88:89] op_sel_hi:[1,0]
	v_pk_mul_f32 v[52:53], v[52:53], v[88:89] op_sel_hi:[1,0]
	v_pk_mul_f32 v[50:51], v[50:51], v[88:89] op_sel_hi:[1,0]
	v_pk_mul_f32 v[48:49], v[48:49], v[88:89] op_sel_hi:[1,0]
	v_pk_mul_f32 v[46:47], v[46:47], v[88:89] op_sel_hi:[1,0]
	v_pk_mul_f32 v[44:45], v[44:45], v[88:89] op_sel_hi:[1,0]
	v_pk_mul_f32 v[42:43], v[42:43], v[88:89] op_sel_hi:[1,0]
	v_pk_mul_f32 v[40:41], v[40:41], v[88:89] op_sel_hi:[1,0]
	v_pk_mul_f32 v[38:39], v[38:39], v[88:89] op_sel_hi:[1,0]
	v_pk_mul_f32 v[36:37], v[36:37], v[88:89] op_sel_hi:[1,0]
	v_pk_mul_f32 v[34:35], v[34:35], v[88:89] op_sel_hi:[1,0]
	v_pk_mul_f32 v[32:33], v[32:33], v[88:89] op_sel_hi:[1,0]
	v_pk_mul_f32 v[30:31], v[30:31], v[88:89] op_sel_hi:[1,0]
	v_pk_mul_f32 v[28:29], v[28:29], v[88:89] op_sel_hi:[1,0]
	v_pk_mul_f32 v[26:27], v[26:27], v[88:89] op_sel_hi:[1,0]
	v_pk_mul_f32 v[24:25], v[24:25], v[88:89] op_sel_hi:[1,0]
	v_pk_mul_f32 v[22:23], v[22:23], v[88:89] op_sel_hi:[1,0]
	v_pk_mul_f32 v[20:21], v[20:21], v[88:89] op_sel_hi:[1,0]
	v_pk_mul_f32 v[18:19], v[18:19], v[88:89] op_sel_hi:[1,0]
	v_pk_mul_f32 v[16:17], v[16:17], v[88:89] op_sel_hi:[1,0]
	v_mul_f32_e32 v197, v197, v88
